# GEMM K-loops: issue next-stage LDS-DMA immediately after the barrier under s_setprio 3, software-pipelined fragment prefetch; diff-attn LDS double buffer
# baseline (speedup 1.0000x reference)
; #define MFMA16(a, b, c) __builtin_amdgcn_mfma_f32_16x16x32_bf16((a), (b), (c), 0, 0, 0)
; DI void vm_wait0() { asm volatile("s_waitcnt vmcnt(0)" ::: "memory"); }
;   DI unsigned koff(int k) const { return (unsigned)((k >> 6) * EIN + (k & 63)); }
; DI void dma16(const void* g, unsigned char* l) { __builtin_amdgcn_global_load_lds((const unsigned*)g, (lds_u32_t*)(unsigned)(size_t)l, 16, 0, 0); }
; template <class AF, class EF>
; DI void gemm_run(unsigned char* lds, int wv, const AF& af, const bf16_t* __restrict__ Bt, int ldb, int M, int N, int K, const EF& ef, int blk_off) {
;     ...
;     for (int kt = 0; kt < nk; ++kt) {
;       unsigned char* cur = sBase + (kt & 1) * GST;
;       if (kt + 1 < nk) {
;         unsigned char* nxt = sBase + ((kt + 1) & 1) * GST;
;         const int k0 = (kt + 1) << 6;
; #pragma unroll
;         for (int i = 0; i < 4; ++i) {
;           dma16(Ab + aoff[i] + af.koff(k0 + cch), nxt + 32768 + (i * 512 + tid) * 16);
;           dma16(Bt + boff[i] + (unsigned)k0, nxt + (i * 512 + tid) * 16);
;         }
;       }
; #pragma unroll
;       for (int ks = 0; ks < 2; ++ks) {
;         bf16x8 wf[4], xf[8];
; #pragma unroll
;         for (int i = 0; i < 4; ++i) wf[i] = *(const bf16x8*)(cur + (wn * 64 + i * 16 + l15) * 128 + (((ks * 4 + q4) ^ swz) * 16));
; #pragma unroll
;         for (int j = 0; j < 8; ++j) xf[j] = *(const bf16x8*)(cur + 32768 + (wm * 128 + j * 16 + l15) * 128 + (((ks * 4 + q4) ^ swz) * 16));
; #pragma unroll
;         for (int i = 0; i < 4; ++i)
; #pragma unroll
;           for (int j = 0; j < 8; ++j) acc[i][j] = MFMA16(wf[i], xf[j], acc[i][j]);
;       }
;       vm_wait0();
;       __syncthreads();
;     }
.Lmyg120_loop:
	s_waitcnt lgkmcnt(7)
	v_mfma_f32_16x16x32_bf16 v[126:129], v[130:133], v[180:183], v[126:129]
	ds_read_b128 v[226:229], v212 offset:10240
	s_waitcnt lgkmcnt(7)
	v_mfma_f32_16x16x32_bf16 v[118:121], v[130:133], v[184:187], v[118:121]
	s_waitcnt lgkmcnt(6)
	v_mfma_f32_16x16x32_bf16 v[110:113], v[130:133], v[188:191], v[110:113]
	s_waitcnt lgkmcnt(5)
	v_mfma_f32_16x16x32_bf16 v[102:105], v[130:133], v[192:195], v[102:105]
	s_waitcnt lgkmcnt(4)
	v_mfma_f32_16x16x32_bf16 v[94:97], v[130:133], v[196:199], v[94:97]
	s_waitcnt lgkmcnt(3)
	v_mfma_f32_16x16x32_bf16 v[86:89], v[130:133], v[200:203], v[86:89]
	s_waitcnt lgkmcnt(2)
	v_mfma_f32_16x16x32_bf16 v[78:81], v[130:133], v[204:207], v[78:81]
	s_waitcnt lgkmcnt(1)
	v_mfma_f32_16x16x32_bf16 v[70:73], v[130:133], v[208:211], v[70:73]
	s_waitcnt lgkmcnt(0)
	v_mfma_f32_16x16x32_bf16 v[122:125], v[226:229], v[180:183], v[122:125]
	ds_read_b128 v[130:133], v212 offset:12288
	v_mfma_f32_16x16x32_bf16 v[114:117], v[226:229], v[184:187], v[114:117]
	v_mfma_f32_16x16x32_bf16 v[106:109], v[226:229], v[188:191], v[106:109]
	v_mfma_f32_16x16x32_bf16 v[98:101], v[226:229], v[192:195], v[98:101]
	v_mfma_f32_16x16x32_bf16 v[90:93], v[226:229], v[196:199], v[90:93]
	v_mfma_f32_16x16x32_bf16 v[82:85], v[226:229], v[200:203], v[82:85]
	v_mfma_f32_16x16x32_bf16 v[74:77], v[226:229], v[204:207], v[74:77]
	v_mfma_f32_16x16x32_bf16 v[66:69], v[226:229], v[208:211], v[66:69]
	s_waitcnt lgkmcnt(0)
	v_mfma_f32_16x16x32_bf16 v[58:61], v[130:133], v[180:183], v[58:61]
	ds_read_b128 v[226:229], v212 offset:14336
	v_mfma_f32_16x16x32_bf16 v[50:53], v[130:133], v[184:187], v[50:53]
	v_add_u32_e32 v0, s100, v179
	v_mfma_f32_16x16x32_bf16 v[42:45], v[130:133], v[188:191], v[42:45]
	v_add3_u32 v212, v0, v176, v177
	v_mfma_f32_16x16x32_bf16 v[34:37], v[130:133], v[192:195], v[34:37]
	v_add3_u32 v0, v0, v178, v177
	v_mfma_f32_16x16x32_bf16 v[26:29], v[130:133], v[196:199], v[26:29]
	v_mfma_f32_16x16x32_bf16 v[18:21], v[130:133], v[200:203], v[18:21]
	v_mfma_f32_16x16x32_bf16 v[6:9], v[130:133], v[204:207], v[6:9]
	v_mfma_f32_16x16x32_bf16 v[2:5], v[130:133], v[208:211], v[2:5]
	s_waitcnt lgkmcnt(0)
	v_mfma_f32_16x16x32_bf16 v[62:65], v[226:229], v[180:183], v[62:65]
	ds_read_b128 v[130:133], v212 offset:8192
	ds_read_b128 v[180:183], v0 offset:40960
	v_mfma_f32_16x16x32_bf16 v[54:57], v[226:229], v[184:187], v[54:57]
	ds_read_b128 v[184:187], v0 offset:43008
	v_mfma_f32_16x16x32_bf16 v[46:49], v[226:229], v[188:191], v[46:49]
	ds_read_b128 v[188:191], v0 offset:45056
	v_mfma_f32_16x16x32_bf16 v[38:41], v[226:229], v[192:195], v[38:41]
	ds_read_b128 v[192:195], v0 offset:47104
	v_mfma_f32_16x16x32_bf16 v[30:33], v[226:229], v[196:199], v[30:33]
	ds_read_b128 v[196:199], v0 offset:49152
	v_mfma_f32_16x16x32_bf16 v[22:25], v[226:229], v[200:203], v[22:25]
	ds_read_b128 v[200:203], v0 offset:51200
	v_mfma_f32_16x16x32_bf16 v[14:17], v[226:229], v[204:207], v[14:17]
	ds_read_b128 v[204:207], v0 offset:53248
	v_mfma_f32_16x16x32_bf16 v[10:13], v[226:229], v[208:211], v[10:13]
	ds_read_b128 v[208:211], v0 offset:55296
	s_waitcnt lgkmcnt(7)
	v_mfma_f32_16x16x32_bf16 v[126:129], v[130:133], v[180:183], v[126:129]
	ds_read_b128 v[226:229], v212 offset:10240
	s_waitcnt lgkmcnt(7)
	v_mfma_f32_16x16x32_bf16 v[118:121], v[130:133], v[184:187], v[118:121]
	s_waitcnt lgkmcnt(6)
	v_mfma_f32_16x16x32_bf16 v[110:113], v[130:133], v[188:191], v[110:113]
	s_waitcnt lgkmcnt(5)
	v_mfma_f32_16x16x32_bf16 v[102:105], v[130:133], v[192:195], v[102:105]
	s_waitcnt lgkmcnt(4)
	v_mfma_f32_16x16x32_bf16 v[94:97], v[130:133], v[196:199], v[94:97]
	s_waitcnt lgkmcnt(3)
	v_mfma_f32_16x16x32_bf16 v[86:89], v[130:133], v[200:203], v[86:89]
	s_waitcnt lgkmcnt(2)
	v_mfma_f32_16x16x32_bf16 v[78:81], v[130:133], v[204:207], v[78:81]
	s_waitcnt lgkmcnt(1)
	v_mfma_f32_16x16x32_bf16 v[70:73], v[130:133], v[208:211], v[70:73]
	s_waitcnt lgkmcnt(0)
	v_mfma_f32_16x16x32_bf16 v[122:125], v[226:229], v[180:183], v[122:125]
	ds_read_b128 v[130:133], v212 offset:12288
	v_mfma_f32_16x16x32_bf16 v[114:117], v[226:229], v[184:187], v[114:117]
	v_mfma_f32_16x16x32_bf16 v[106:109], v[226:229], v[188:191], v[106:109]
	v_mfma_f32_16x16x32_bf16 v[98:101], v[226:229], v[192:195], v[98:101]
	v_mfma_f32_16x16x32_bf16 v[90:93], v[226:229], v[196:199], v[90:93]
	v_mfma_f32_16x16x32_bf16 v[82:85], v[226:229], v[200:203], v[82:85]
	v_mfma_f32_16x16x32_bf16 v[74:77], v[226:229], v[204:207], v[74:77]
	v_mfma_f32_16x16x32_bf16 v[66:69], v[226:229], v[208:211], v[66:69]
	s_waitcnt lgkmcnt(0)
	v_mfma_f32_16x16x32_bf16 v[58:61], v[130:133], v[180:183], v[58:61]
	ds_read_b128 v[226:229], v212 offset:14336
	v_mfma_f32_16x16x32_bf16 v[50:53], v[130:133], v[184:187], v[50:53]
	v_mfma_f32_16x16x32_bf16 v[42:45], v[130:133], v[188:191], v[42:45]
	v_mfma_f32_16x16x32_bf16 v[34:37], v[130:133], v[192:195], v[34:37]
	v_mfma_f32_16x16x32_bf16 v[26:29], v[130:133], v[196:199], v[26:29]
	v_mfma_f32_16x16x32_bf16 v[18:21], v[130:133], v[200:203], v[18:21]
	v_mfma_f32_16x16x32_bf16 v[6:9], v[130:133], v[204:207], v[6:9]
	v_mfma_f32_16x16x32_bf16 v[2:5], v[130:133], v[208:211], v[2:5]
	s_waitcnt vmcnt(0) lgkmcnt(0)
	s_barrier
	s_add_u32 s4, s4, 0x80
	s_addc_u32 s5, s5, 0
	s_add_i32 s14, s14, 0x10000
	s_cmpk_eq_i32 s4, 0x800
	s_cbranch_scc1 .Lmyg120_tail
	s_add_i32 s100, s14, 0xffff0000
	s_and_b32 s100, s100, 0x10000
	v_add_u32_e32 v0, s100, v175
	v_add3_u32 v212, v0, v176, v177
	v_add3_u32 v0, v0, v178, v177
	s_cmpk_eq_i32 s4, 0x780
	s_cbranch_scc1 .Lmyg120_nodma
	s_setprio 3
	s_and_b32 s15, s14, 0x10000
	s_add_i32 s15, s15, 0
	s_add_i32 s16, s15, 0x2000
	s_add_i32 s15, s15, 0xa000
	v_add_u32_e32 v224, s15, v136
	v_lshl_add_u64 v[222:223], v[160:161], 0, s[4:5]
	v_readfirstlane_b32 s17, v224
	v_add_u32_e32 v224, s16, v136
	s_mov_b32 m0, s17
	v_readfirstlane_b32 s17, v224
	v_add_u32_e32 v224, s15, v138
	global_load_lds_dwordx4 v[222:223], off
	v_lshl_add_u64 v[222:223], v[152:153], 0, s[4:5]
	s_mov_b32 m0, s17
	v_readfirstlane_b32 s17, v224
	v_add_u32_e32 v224, s16, v138
	global_load_lds_dwordx4 v[222:223], off
	v_lshl_add_u64 v[222:223], v[158:159], 0, s[4:5]
	s_mov_b32 m0, s17
	v_readfirstlane_b32 s17, v224
	v_add_u32_e32 v224, s15, v140
	global_load_lds_dwordx4 v[222:223], off
	v_lshl_add_u64 v[222:223], v[150:151], 0, s[4:5]
	s_mov_b32 m0, s17
	v_readfirstlane_b32 s17, v224
	v_add_u32_e32 v224, s16, v140
	global_load_lds_dwordx4 v[222:223], off
	v_lshl_add_u64 v[222:223], v[156:157], 0, s[4:5]
	s_mov_b32 m0, s17
	v_readfirstlane_b32 s17, v224
	v_add_u32_e32 v224, s15, v142
	global_load_lds_dwordx4 v[222:223], off
	v_lshl_add_u64 v[222:223], v[148:149], 0, s[4:5]
	s_mov_b32 m0, s17
	v_readfirstlane_b32 s15, v224
	v_add_u32_e32 v224, s16, v142
	global_load_lds_dwordx4 v[222:223], off
	v_lshl_add_u64 v[222:223], v[154:155], 0, s[4:5]
	s_mov_b32 m0, s15
	v_readfirstlane_b32 s15, v224
	global_load_lds_dwordx4 v[222:223], off
	v_lshl_add_u64 v[222:223], v[146:147], 0, s[4:5]
	s_mov_b32 m0, s15
	s_nop 0
	global_load_lds_dwordx4 v[222:223], off
	s_setprio 0
; #define MFMA16(a, b, c) __builtin_amdgcn_mfma_f32_16x16x32_bf16((a), (b), (c), 0, 0, 0)
; DI void vm_wait0() { asm volatile("s_waitcnt vmcnt(0)" ::: "memory"); }
;   DI unsigned koff(int k) const { return (unsigned)((k >> 6) * EIN + (k & 63)); }
; DI void dma16(const void* g, unsigned char* l) { __builtin_amdgcn_global_load_lds((const unsigned*)g, (lds_u32_t*)(unsigned)(size_t)l, 16, 0, 0); }
; template <class AF, class EF>
; DI void gemm_run(unsigned char* lds, int wv, const AF& af, const bf16_t* __restrict__ Bt, int ldb, int M, int N, int K, const EF& ef, int blk_off) {
;     ...
;     for (int kt = 0; kt < nk; ++kt) {
;       unsigned char* cur = sBase + (kt & 1) * GST;
;       if (kt + 1 < nk) {
;         unsigned char* nxt = sBase + ((kt + 1) & 1) * GST;
;         const int k0 = (kt + 1) << 6;
; #pragma unroll
;         for (int i = 0; i < 4; ++i) {
;           dma16(Ab + aoff[i] + af.koff(k0 + cch), nxt + 32768 + (i * 512 + tid) * 16);
;           dma16(Bt + boff[i] + (unsigned)k0, nxt + (i * 512 + tid) * 16);
;         }
;       }
; #pragma unroll
;       for (int ks = 0; ks < 2; ++ks) {
;         bf16x8 wf[4], xf[8];
; #pragma unroll
;         for (int i = 0; i < 4; ++i) wf[i] = *(const bf16x8*)(cur + (wn * 64 + i * 16 + l15) * 128 + (((ks * 4 + q4) ^ swz) * 16));
; #pragma unroll
;         for (int j = 0; j < 8; ++j) xf[j] = *(const bf16x8*)(cur + 32768 + (wm * 128 + j * 16 + l15) * 128 + (((ks * 4 + q4) ^ swz) * 16));
; #pragma unroll
;         for (int i = 0; i < 4; ++i)
; #pragma unroll
;           for (int j = 0; j < 8; ++j) acc[i][j] = MFMA16(wf[i], xf[j], acc[i][j]);
;       }
;       vm_wait0();
;       __syncthreads();
;     }
.Lmyg120_nodma:
	v_mfma_f32_16x16x32_bf16 v[62:65], v[226:229], v[180:183], v[62:65]
	ds_read_b128 v[130:133], v212 offset:8192
	ds_read_b128 v[180:183], v0 offset:40960
	v_mfma_f32_16x16x32_bf16 v[54:57], v[226:229], v[184:187], v[54:57]
	ds_read_b128 v[184:187], v0 offset:43008
	v_mfma_f32_16x16x32_bf16 v[46:49], v[226:229], v[188:191], v[46:49]
	ds_read_b128 v[188:191], v0 offset:45056
	v_mfma_f32_16x16x32_bf16 v[38:41], v[226:229], v[192:195], v[38:41]
	ds_read_b128 v[192:195], v0 offset:47104
	v_mfma_f32_16x16x32_bf16 v[30:33], v[226:229], v[196:199], v[30:33]
	ds_read_b128 v[196:199], v0 offset:49152
	v_mfma_f32_16x16x32_bf16 v[22:25], v[226:229], v[200:203], v[22:25]
	ds_read_b128 v[200:203], v0 offset:51200
	v_mfma_f32_16x16x32_bf16 v[14:17], v[226:229], v[204:207], v[14:17]
	ds_read_b128 v[204:207], v0 offset:53248
	v_mfma_f32_16x16x32_bf16 v[10:13], v[226:229], v[208:211], v[10:13]
	ds_read_b128 v[208:211], v0 offset:55296
	s_branch .Lmyg120_loop

; #define MFMA16(a, b, c) __builtin_amdgcn_mfma_f32_16x16x32_bf16((a), (b), (c), 0, 0, 0)
; DI void vm_wait0() { asm volatile("s_waitcnt vmcnt(0)" ::: "memory"); }
;   DI unsigned koff(int k) const { return (unsigned)((k >> 6) * EIN + (k & 63)); }
; DI void dma16(const void* g, unsigned char* l) { __builtin_amdgcn_global_load_lds((const unsigned*)g, (lds_u32_t*)(unsigned)(size_t)l, 16, 0, 0); }
; template <class AF, class EF>
; DI void gemm_run(unsigned char* lds, int wv, const AF& af, const bf16_t* __restrict__ Bt, int ldb, int M, int N, int K, const EF& ef, int blk_off) {
;     ...
;     for (int kt = 0; kt < nk; ++kt) {
;       unsigned char* cur = sBase + (kt & 1) * GST;
;       if (kt + 1 < nk) {
;         unsigned char* nxt = sBase + ((kt + 1) & 1) * GST;
;         const int k0 = (kt + 1) << 6;
; #pragma unroll
;         for (int i = 0; i < 4; ++i) {
;           dma16(Ab + aoff[i] + af.koff(k0 + cch), nxt + 32768 + (i * 512 + tid) * 16);
;           dma16(Bt + boff[i] + (unsigned)k0, nxt + (i * 512 + tid) * 16);
;         }
;       }
; #pragma unroll
;       for (int ks = 0; ks < 2; ++ks) {
;         bf16x8 wf[4], xf[8];
; #pragma unroll
;         for (int i = 0; i < 4; ++i) wf[i] = *(const bf16x8*)(cur + (wn * 64 + i * 16 + l15) * 128 + (((ks * 4 + q4) ^ swz) * 16));
; #pragma unroll
;         for (int j = 0; j < 8; ++j) xf[j] = *(const bf16x8*)(cur + 32768 + (wm * 128 + j * 16 + l15) * 128 + (((ks * 4 + q4) ^ swz) * 16));
; #pragma unroll
;         for (int i = 0; i < 4; ++i)
; #pragma unroll
;           for (int j = 0; j < 8; ++j) acc[i][j] = MFMA16(wf[i], xf[j], acc[i][j]);
;       }
;       vm_wait0();
;       __syncthreads();
;     }
.Lmyg261_loop:
	s_waitcnt lgkmcnt(7)
	v_mfma_f32_16x16x32_bf16 v[126:129], v[130:133], v[180:183], v[126:129]
	ds_read_b128 v[226:229], v212 offset:10240
	s_waitcnt lgkmcnt(7)
	v_mfma_f32_16x16x32_bf16 v[118:121], v[130:133], v[184:187], v[118:121]
	s_waitcnt lgkmcnt(6)
	v_mfma_f32_16x16x32_bf16 v[110:113], v[130:133], v[188:191], v[110:113]
	s_waitcnt lgkmcnt(5)
	v_mfma_f32_16x16x32_bf16 v[102:105], v[130:133], v[192:195], v[102:105]
	s_waitcnt lgkmcnt(4)
	v_mfma_f32_16x16x32_bf16 v[94:97], v[130:133], v[196:199], v[94:97]
	s_waitcnt lgkmcnt(3)
	v_mfma_f32_16x16x32_bf16 v[86:89], v[130:133], v[200:203], v[86:89]
	s_waitcnt lgkmcnt(2)
	v_mfma_f32_16x16x32_bf16 v[78:81], v[130:133], v[204:207], v[78:81]
	s_waitcnt lgkmcnt(1)
	v_mfma_f32_16x16x32_bf16 v[70:73], v[130:133], v[208:211], v[70:73]
	s_waitcnt lgkmcnt(0)
	v_mfma_f32_16x16x32_bf16 v[122:125], v[226:229], v[180:183], v[122:125]
	ds_read_b128 v[130:133], v212 offset:12288
	v_mfma_f32_16x16x32_bf16 v[114:117], v[226:229], v[184:187], v[114:117]
	v_mfma_f32_16x16x32_bf16 v[106:109], v[226:229], v[188:191], v[106:109]
	v_mfma_f32_16x16x32_bf16 v[98:101], v[226:229], v[192:195], v[98:101]
	v_mfma_f32_16x16x32_bf16 v[90:93], v[226:229], v[196:199], v[90:93]
	v_mfma_f32_16x16x32_bf16 v[82:85], v[226:229], v[200:203], v[82:85]
	v_mfma_f32_16x16x32_bf16 v[74:77], v[226:229], v[204:207], v[74:77]
	v_mfma_f32_16x16x32_bf16 v[66:69], v[226:229], v[208:211], v[66:69]
	s_waitcnt lgkmcnt(0)
	v_mfma_f32_16x16x32_bf16 v[62:65], v[130:133], v[180:183], v[62:65]
	ds_read_b128 v[226:229], v212 offset:14336
	v_mfma_f32_16x16x32_bf16 v[54:57], v[130:133], v[184:187], v[54:57]
	v_add_u32_e32 v0, s100, v179
	v_mfma_f32_16x16x32_bf16 v[46:49], v[130:133], v[188:191], v[46:49]
	v_add3_u32 v212, v0, v176, v177
	v_mfma_f32_16x16x32_bf16 v[38:41], v[130:133], v[192:195], v[38:41]
	v_add3_u32 v0, v0, v178, v177
	v_mfma_f32_16x16x32_bf16 v[30:33], v[130:133], v[196:199], v[30:33]
	v_mfma_f32_16x16x32_bf16 v[22:25], v[130:133], v[200:203], v[22:25]
	v_mfma_f32_16x16x32_bf16 v[14:17], v[130:133], v[204:207], v[14:17]
	v_mfma_f32_16x16x32_bf16 v[2:5], v[130:133], v[208:211], v[2:5]
	s_waitcnt lgkmcnt(0)
	v_mfma_f32_16x16x32_bf16 v[58:61], v[226:229], v[180:183], v[58:61]
	ds_read_b128 v[130:133], v212 offset:8192
	ds_read_b128 v[180:183], v0 offset:40960
	v_mfma_f32_16x16x32_bf16 v[50:53], v[226:229], v[184:187], v[50:53]
	ds_read_b128 v[184:187], v0 offset:43008
	v_mfma_f32_16x16x32_bf16 v[42:45], v[226:229], v[188:191], v[42:45]
	ds_read_b128 v[188:191], v0 offset:45056
	v_mfma_f32_16x16x32_bf16 v[34:37], v[226:229], v[192:195], v[34:37]
	ds_read_b128 v[192:195], v0 offset:47104
	v_mfma_f32_16x16x32_bf16 v[26:29], v[226:229], v[196:199], v[26:29]
	ds_read_b128 v[196:199], v0 offset:49152
	v_mfma_f32_16x16x32_bf16 v[18:21], v[226:229], v[200:203], v[18:21]
	ds_read_b128 v[200:203], v0 offset:51200
	v_mfma_f32_16x16x32_bf16 v[10:13], v[226:229], v[204:207], v[10:13]
	ds_read_b128 v[204:207], v0 offset:53248
	v_mfma_f32_16x16x32_bf16 v[6:9], v[226:229], v[208:211], v[6:9]
	ds_read_b128 v[208:211], v0 offset:55296
	s_waitcnt lgkmcnt(7)
	v_mfma_f32_16x16x32_bf16 v[126:129], v[130:133], v[180:183], v[126:129]
	ds_read_b128 v[226:229], v212 offset:10240
	s_waitcnt lgkmcnt(7)
	v_mfma_f32_16x16x32_bf16 v[118:121], v[130:133], v[184:187], v[118:121]
	s_waitcnt lgkmcnt(6)
	v_mfma_f32_16x16x32_bf16 v[110:113], v[130:133], v[188:191], v[110:113]
	s_waitcnt lgkmcnt(5)
	v_mfma_f32_16x16x32_bf16 v[102:105], v[130:133], v[192:195], v[102:105]
	s_waitcnt lgkmcnt(4)
	v_mfma_f32_16x16x32_bf16 v[94:97], v[130:133], v[196:199], v[94:97]
	s_waitcnt lgkmcnt(3)
	v_mfma_f32_16x16x32_bf16 v[86:89], v[130:133], v[200:203], v[86:89]
	s_waitcnt lgkmcnt(2)
	v_mfma_f32_16x16x32_bf16 v[78:81], v[130:133], v[204:207], v[78:81]
	s_waitcnt lgkmcnt(1)
	v_mfma_f32_16x16x32_bf16 v[70:73], v[130:133], v[208:211], v[70:73]
	s_waitcnt lgkmcnt(0)
	v_mfma_f32_16x16x32_bf16 v[122:125], v[226:229], v[180:183], v[122:125]
	ds_read_b128 v[130:133], v212 offset:12288
	v_mfma_f32_16x16x32_bf16 v[114:117], v[226:229], v[184:187], v[114:117]
	v_mfma_f32_16x16x32_bf16 v[106:109], v[226:229], v[188:191], v[106:109]
	v_mfma_f32_16x16x32_bf16 v[98:101], v[226:229], v[192:195], v[98:101]
	v_mfma_f32_16x16x32_bf16 v[90:93], v[226:229], v[196:199], v[90:93]
	v_mfma_f32_16x16x32_bf16 v[82:85], v[226:229], v[200:203], v[82:85]
	v_mfma_f32_16x16x32_bf16 v[74:77], v[226:229], v[204:207], v[74:77]
	v_mfma_f32_16x16x32_bf16 v[66:69], v[226:229], v[208:211], v[66:69]
	s_waitcnt lgkmcnt(0)
	v_mfma_f32_16x16x32_bf16 v[62:65], v[130:133], v[180:183], v[62:65]
	ds_read_b128 v[226:229], v212 offset:14336
	v_mfma_f32_16x16x32_bf16 v[54:57], v[130:133], v[184:187], v[54:57]
	v_mfma_f32_16x16x32_bf16 v[46:49], v[130:133], v[188:191], v[46:49]
	v_mfma_f32_16x16x32_bf16 v[38:41], v[130:133], v[192:195], v[38:41]
	v_mfma_f32_16x16x32_bf16 v[30:33], v[130:133], v[196:199], v[30:33]
	v_mfma_f32_16x16x32_bf16 v[22:25], v[130:133], v[200:203], v[22:25]
	v_mfma_f32_16x16x32_bf16 v[14:17], v[130:133], v[204:207], v[14:17]
	v_mfma_f32_16x16x32_bf16 v[2:5], v[130:133], v[208:211], v[2:5]
	s_waitcnt vmcnt(0) lgkmcnt(0)
	s_barrier
	s_add_u32 s4, s4, 0x80
	s_addc_u32 s5, s5, 0
	s_add_i32 s16, s16, 0x10000
	s_cmpk_eq_i32 s4, 0x800
	s_cbranch_scc1 .Lmyg261_tail
	s_add_i32 s100, s16, 0xffff0000
	s_and_b32 s100, s100, 0x10000
	v_add_u32_e32 v0, s100, v175
	v_add3_u32 v212, v0, v176, v177
	v_add3_u32 v0, v0, v178, v177
	s_cmpk_eq_i32 s4, 0x780
	s_cbranch_scc1 .Lmyg261_nodma
	s_setprio 3
	s_and_b32 s17, s16, 0x10000
	s_add_i32 s17, s17, 0
	s_add_i32 s18, s17, 0x2000
	s_add_i32 s17, s17, 0xa000
	v_add_u32_e32 v224, s17, v136
	v_lshl_add_u64 v[222:223], v[160:161], 0, s[4:5]
	v_readfirstlane_b32 s19, v224
	v_add_u32_e32 v224, s18, v136
	s_mov_b32 m0, s19
	v_readfirstlane_b32 s19, v224
	v_add_u32_e32 v224, s17, v138
	global_load_lds_dwordx4 v[222:223], off
	v_lshl_add_u64 v[222:223], v[152:153], 0, s[4:5]
	s_mov_b32 m0, s19
	v_readfirstlane_b32 s19, v224
	v_add_u32_e32 v224, s18, v138
	global_load_lds_dwordx4 v[222:223], off
	v_lshl_add_u64 v[222:223], v[158:159], 0, s[4:5]
	s_mov_b32 m0, s19
	v_readfirstlane_b32 s19, v224
	v_add_u32_e32 v224, s17, v140
	global_load_lds_dwordx4 v[222:223], off
	v_lshl_add_u64 v[222:223], v[150:151], 0, s[4:5]
	s_mov_b32 m0, s19
	v_readfirstlane_b32 s19, v224
	v_add_u32_e32 v224, s18, v140
	global_load_lds_dwordx4 v[222:223], off
	v_lshl_add_u64 v[222:223], v[156:157], 0, s[4:5]
	s_mov_b32 m0, s19
	v_readfirstlane_b32 s19, v224
	v_add_u32_e32 v224, s17, v142
	global_load_lds_dwordx4 v[222:223], off
	v_lshl_add_u64 v[222:223], v[148:149], 0, s[4:5]
	s_mov_b32 m0, s19
	v_readfirstlane_b32 s17, v224
	v_add_u32_e32 v224, s18, v142
	global_load_lds_dwordx4 v[222:223], off
	v_lshl_add_u64 v[222:223], v[154:155], 0, s[4:5]
	s_mov_b32 m0, s17
	v_readfirstlane_b32 s17, v224
	global_load_lds_dwordx4 v[222:223], off
	v_lshl_add_u64 v[222:223], v[146:147], 0, s[4:5]
	s_mov_b32 m0, s17
	s_nop 0
	global_load_lds_dwordx4 v[222:223], off
	s_setprio 0
; #define MFMA16(a, b, c) __builtin_amdgcn_mfma_f32_16x16x32_bf16((a), (b), (c), 0, 0, 0)
; DI void vm_wait0() { asm volatile("s_waitcnt vmcnt(0)" ::: "memory"); }
;   DI unsigned koff(int k) const { return (unsigned)((k >> 6) * EIN + (k & 63)); }
; DI void dma16(const void* g, unsigned char* l) { __builtin_amdgcn_global_load_lds((const unsigned*)g, (lds_u32_t*)(unsigned)(size_t)l, 16, 0, 0); }
; template <class AF, class EF>
; DI void gemm_run(unsigned char* lds, int wv, const AF& af, const bf16_t* __restrict__ Bt, int ldb, int M, int N, int K, const EF& ef, int blk_off) {
;     ...
;     for (int kt = 0; kt < nk; ++kt) {
;       unsigned char* cur = sBase + (kt & 1) * GST;
;       if (kt + 1 < nk) {
;         unsigned char* nxt = sBase + ((kt + 1) & 1) * GST;
;         const int k0 = (kt + 1) << 6;
; #pragma unroll
;         for (int i = 0; i < 4; ++i) {
;           dma16(Ab + aoff[i] + af.koff(k0 + cch), nxt + 32768 + (i * 512 + tid) * 16);
;           dma16(Bt + boff[i] + (unsigned)k0, nxt + (i * 512 + tid) * 16);
;         }
;       }
; #pragma unroll
;       for (int ks = 0; ks < 2; ++ks) {
;         bf16x8 wf[4], xf[8];
; #pragma unroll
;         for (int i = 0; i < 4; ++i) wf[i] = *(const bf16x8*)(cur + (wn * 64 + i * 16 + l15) * 128 + (((ks * 4 + q4) ^ swz) * 16));
; #pragma unroll
;         for (int j = 0; j < 8; ++j) xf[j] = *(const bf16x8*)(cur + 32768 + (wm * 128 + j * 16 + l15) * 128 + (((ks * 4 + q4) ^ swz) * 16));
; #pragma unroll
;         for (int i = 0; i < 4; ++i)
; #pragma unroll
;           for (int j = 0; j < 8; ++j) acc[i][j] = MFMA16(wf[i], xf[j], acc[i][j]);
;       }
;       vm_wait0();
;       __syncthreads();
;     }
.Lmyg261_nodma:
	v_mfma_f32_16x16x32_bf16 v[58:61], v[226:229], v[180:183], v[58:61]
	ds_read_b128 v[130:133], v212 offset:8192
	ds_read_b128 v[180:183], v0 offset:40960
	v_mfma_f32_16x16x32_bf16 v[50:53], v[226:229], v[184:187], v[50:53]
	ds_read_b128 v[184:187], v0 offset:43008
	v_mfma_f32_16x16x32_bf16 v[42:45], v[226:229], v[188:191], v[42:45]
	ds_read_b128 v[188:191], v0 offset:45056
	v_mfma_f32_16x16x32_bf16 v[34:37], v[226:229], v[192:195], v[34:37]
	ds_read_b128 v[192:195], v0 offset:47104
	v_mfma_f32_16x16x32_bf16 v[26:29], v[226:229], v[196:199], v[26:29]
	ds_read_b128 v[196:199], v0 offset:49152
	v_mfma_f32_16x16x32_bf16 v[18:21], v[226:229], v[200:203], v[18:21]
	ds_read_b128 v[200:203], v0 offset:51200
	v_mfma_f32_16x16x32_bf16 v[10:13], v[226:229], v[204:207], v[10:13]
	ds_read_b128 v[204:207], v0 offset:53248
	v_mfma_f32_16x16x32_bf16 v[6:9], v[226:229], v[208:211], v[6:9]
	ds_read_b128 v[208:211], v0 offset:55296
	s_branch .Lmyg261_loop

; #define MFMA16(a, b, c) __builtin_amdgcn_mfma_f32_16x16x32_bf16((a), (b), (c), 0, 0, 0)
; DI void vm_wait0() { asm volatile("s_waitcnt vmcnt(0)" ::: "memory"); }
;   DI unsigned koff(int k) const { return (unsigned)((k >> 6) * EIN + (k & 63)); }
; DI void dma16(const void* g, unsigned char* l) { __builtin_amdgcn_global_load_lds((const unsigned*)g, (lds_u32_t*)(unsigned)(size_t)l, 16, 0, 0); }
; template <class AF, class EF>
; DI void gemm_run(unsigned char* lds, int wv, const AF& af, const bf16_t* __restrict__ Bt, int ldb, int M, int N, int K, const EF& ef, int blk_off) {
;     ...
;     for (int kt = 0; kt < nk; ++kt) {
;       unsigned char* cur = sBase + (kt & 1) * GST;
;       if (kt + 1 < nk) {
;         unsigned char* nxt = sBase + ((kt + 1) & 1) * GST;
;         const int k0 = (kt + 1) << 6;
; #pragma unroll
;         for (int i = 0; i < 4; ++i) {
;           dma16(Ab + aoff[i] + af.koff(k0 + cch), nxt + 32768 + (i * 512 + tid) * 16);
;           dma16(Bt + boff[i] + (unsigned)k0, nxt + (i * 512 + tid) * 16);
;         }
;       }
; #pragma unroll
;       for (int ks = 0; ks < 2; ++ks) {
;         bf16x8 wf[4], xf[8];
; #pragma unroll
;         for (int i = 0; i < 4; ++i) wf[i] = *(const bf16x8*)(cur + (wn * 64 + i * 16 + l15) * 128 + (((ks * 4 + q4) ^ swz) * 16));
; #pragma unroll
;         for (int j = 0; j < 8; ++j) xf[j] = *(const bf16x8*)(cur + 32768 + (wm * 128 + j * 16 + l15) * 128 + (((ks * 4 + q4) ^ swz) * 16));
; #pragma unroll
;         for (int i = 0; i < 4; ++i)
; #pragma unroll
;           for (int j = 0; j < 8; ++j) acc[i][j] = MFMA16(wf[i], xf[j], acc[i][j]);
;       }
;       vm_wait0();
;       __syncthreads();
;     }
.Lmyg1245_loop:
	s_waitcnt lgkmcnt(7)
	v_mfma_f32_16x16x32_bf16 v[118:121], v[130:133], v[184:187], v[118:121]
	ds_read_b128 v[226:229], v212 offset:10240
	s_waitcnt lgkmcnt(7)
	v_mfma_f32_16x16x32_bf16 v[126:129], v[130:133], v[134:137], v[126:129]
	s_waitcnt lgkmcnt(6)
	v_mfma_f32_16x16x32_bf16 v[110:113], v[130:133], v[188:191], v[110:113]
	s_waitcnt lgkmcnt(5)
	v_mfma_f32_16x16x32_bf16 v[102:105], v[130:133], v[192:195], v[102:105]
	s_waitcnt lgkmcnt(4)
	v_mfma_f32_16x16x32_bf16 v[94:97], v[130:133], v[196:199], v[94:97]
	s_waitcnt lgkmcnt(3)
	v_mfma_f32_16x16x32_bf16 v[86:89], v[130:133], v[200:203], v[86:89]
	s_waitcnt lgkmcnt(2)
	v_mfma_f32_16x16x32_bf16 v[78:81], v[130:133], v[204:207], v[78:81]
	s_waitcnt lgkmcnt(1)
	v_mfma_f32_16x16x32_bf16 v[70:73], v[130:133], v[208:211], v[70:73]
	s_waitcnt lgkmcnt(0)
	v_mfma_f32_16x16x32_bf16 v[122:125], v[226:229], v[134:137], v[122:125]
	ds_read_b128 v[130:133], v212 offset:12288
	v_mfma_f32_16x16x32_bf16 v[114:117], v[226:229], v[184:187], v[114:117]
	v_mfma_f32_16x16x32_bf16 v[106:109], v[226:229], v[188:191], v[106:109]
	v_mfma_f32_16x16x32_bf16 v[98:101], v[226:229], v[192:195], v[98:101]
	v_mfma_f32_16x16x32_bf16 v[90:93], v[226:229], v[196:199], v[90:93]
	v_mfma_f32_16x16x32_bf16 v[82:85], v[226:229], v[200:203], v[82:85]
	v_mfma_f32_16x16x32_bf16 v[74:77], v[226:229], v[204:207], v[74:77]
	v_mfma_f32_16x16x32_bf16 v[66:69], v[226:229], v[208:211], v[66:69]
	s_waitcnt lgkmcnt(0)
	v_mfma_f32_16x16x32_bf16 v[58:61], v[130:133], v[134:137], v[58:61]
	ds_read_b128 v[226:229], v212 offset:14336
	v_mfma_f32_16x16x32_bf16 v[50:53], v[130:133], v[184:187], v[50:53]
	v_add_u32_e32 v0, s100, v183
	v_mfma_f32_16x16x32_bf16 v[42:45], v[130:133], v[188:191], v[42:45]
	v_add3_u32 v212, v0, v180, v181
	v_mfma_f32_16x16x32_bf16 v[30:33], v[130:133], v[192:195], v[30:33]
	v_add3_u32 v0, v0, v182, v181
	v_mfma_f32_16x16x32_bf16 v[14:17], v[130:133], v[196:199], v[14:17]
	v_mfma_f32_16x16x32_bf16 v[10:13], v[130:133], v[200:203], v[10:13]
	v_mfma_f32_16x16x32_bf16 v[6:9], v[130:133], v[204:207], v[6:9]
	v_mfma_f32_16x16x32_bf16 v[2:5], v[130:133], v[208:211], v[2:5]
	s_waitcnt lgkmcnt(0)
	v_mfma_f32_16x16x32_bf16 v[54:57], v[226:229], v[184:187], v[54:57]
	ds_read_b128 v[130:133], v212 offset:8192
	ds_read_b128 v[184:187], v0 offset:43008
	v_mfma_f32_16x16x32_bf16 v[62:65], v[226:229], v[134:137], v[62:65]
	ds_read_b128 v[134:137], v0 offset:40960
	v_mfma_f32_16x16x32_bf16 v[46:49], v[226:229], v[188:191], v[46:49]
	ds_read_b128 v[188:191], v0 offset:45056
	v_mfma_f32_16x16x32_bf16 v[38:41], v[226:229], v[192:195], v[38:41]
	ds_read_b128 v[192:195], v0 offset:47104
	v_mfma_f32_16x16x32_bf16 v[26:29], v[226:229], v[196:199], v[26:29]
	ds_read_b128 v[196:199], v0 offset:49152
	v_mfma_f32_16x16x32_bf16 v[22:25], v[226:229], v[200:203], v[22:25]
	ds_read_b128 v[200:203], v0 offset:51200
	v_mfma_f32_16x16x32_bf16 v[34:37], v[226:229], v[204:207], v[34:37]
	ds_read_b128 v[204:207], v0 offset:53248
	v_mfma_f32_16x16x32_bf16 v[18:21], v[226:229], v[208:211], v[18:21]
	ds_read_b128 v[208:211], v0 offset:55296
	s_waitcnt lgkmcnt(7)
	v_mfma_f32_16x16x32_bf16 v[118:121], v[130:133], v[184:187], v[118:121]
	ds_read_b128 v[226:229], v212 offset:10240
	s_waitcnt lgkmcnt(7)
	v_mfma_f32_16x16x32_bf16 v[126:129], v[130:133], v[134:137], v[126:129]
	s_waitcnt lgkmcnt(6)
	v_mfma_f32_16x16x32_bf16 v[110:113], v[130:133], v[188:191], v[110:113]
	s_waitcnt lgkmcnt(5)
	v_mfma_f32_16x16x32_bf16 v[102:105], v[130:133], v[192:195], v[102:105]
	s_waitcnt lgkmcnt(4)
	v_mfma_f32_16x16x32_bf16 v[94:97], v[130:133], v[196:199], v[94:97]
	s_waitcnt lgkmcnt(3)
	v_mfma_f32_16x16x32_bf16 v[86:89], v[130:133], v[200:203], v[86:89]
	s_waitcnt lgkmcnt(2)
	v_mfma_f32_16x16x32_bf16 v[78:81], v[130:133], v[204:207], v[78:81]
	s_waitcnt lgkmcnt(1)
	v_mfma_f32_16x16x32_bf16 v[70:73], v[130:133], v[208:211], v[70:73]
	s_waitcnt lgkmcnt(0)
	v_mfma_f32_16x16x32_bf16 v[122:125], v[226:229], v[134:137], v[122:125]
	ds_read_b128 v[130:133], v212 offset:12288
	v_mfma_f32_16x16x32_bf16 v[114:117], v[226:229], v[184:187], v[114:117]
	v_mfma_f32_16x16x32_bf16 v[106:109], v[226:229], v[188:191], v[106:109]
	v_mfma_f32_16x16x32_bf16 v[98:101], v[226:229], v[192:195], v[98:101]
	v_mfma_f32_16x16x32_bf16 v[90:93], v[226:229], v[196:199], v[90:93]
	v_mfma_f32_16x16x32_bf16 v[82:85], v[226:229], v[200:203], v[82:85]
	v_mfma_f32_16x16x32_bf16 v[74:77], v[226:229], v[204:207], v[74:77]
	v_mfma_f32_16x16x32_bf16 v[66:69], v[226:229], v[208:211], v[66:69]
	s_waitcnt lgkmcnt(0)
	v_mfma_f32_16x16x32_bf16 v[58:61], v[130:133], v[134:137], v[58:61]
	ds_read_b128 v[226:229], v212 offset:14336
	v_mfma_f32_16x16x32_bf16 v[50:53], v[130:133], v[184:187], v[50:53]
	v_mfma_f32_16x16x32_bf16 v[42:45], v[130:133], v[188:191], v[42:45]
	v_mfma_f32_16x16x32_bf16 v[30:33], v[130:133], v[192:195], v[30:33]
	v_mfma_f32_16x16x32_bf16 v[14:17], v[130:133], v[196:199], v[14:17]
	v_mfma_f32_16x16x32_bf16 v[10:13], v[130:133], v[200:203], v[10:13]
	v_mfma_f32_16x16x32_bf16 v[6:9], v[130:133], v[204:207], v[6:9]
	v_mfma_f32_16x16x32_bf16 v[2:5], v[130:133], v[208:211], v[2:5]
	s_waitcnt vmcnt(0) lgkmcnt(0)
	s_barrier
; #define MFMA16(a, b, c) __builtin_amdgcn_mfma_f32_16x16x32_bf16((a), (b), (c), 0, 0, 0)
; DI void vm_wait0() { asm volatile("s_waitcnt vmcnt(0)" ::: "memory"); }
;   DI unsigned koff(int k) const { return (unsigned)((k >> 6) * EIN + (k & 63)); }
; DI void dma16(const void* g, unsigned char* l) { __builtin_amdgcn_global_load_lds((const unsigned*)g, (lds_u32_t*)(unsigned)(size_t)l, 16, 0, 0); }
; template <class AF, class EF>
; DI void gemm_run(unsigned char* lds, int wv, const AF& af, const bf16_t* __restrict__ Bt, int ldb, int M, int N, int K, const EF& ef, int blk_off) {
;     ...
;     for (int kt = 0; kt < nk; ++kt) {
;       unsigned char* cur = sBase + (kt & 1) * GST;
;       if (kt + 1 < nk) {
;         unsigned char* nxt = sBase + ((kt + 1) & 1) * GST;
;         const int k0 = (kt + 1) << 6;
; #pragma unroll
;         for (int i = 0; i < 4; ++i) {
;           dma16(Ab + aoff[i] + af.koff(k0 + cch), nxt + 32768 + (i * 512 + tid) * 16);
;           dma16(Bt + boff[i] + (unsigned)k0, nxt + (i * 512 + tid) * 16);
;         }
;       }
; #pragma unroll
;       for (int ks = 0; ks < 2; ++ks) {
;         bf16x8 wf[4], xf[8];
; #pragma unroll
;         for (int i = 0; i < 4; ++i) wf[i] = *(const bf16x8*)(cur + (wn * 64 + i * 16 + l15) * 128 + (((ks * 4 + q4) ^ swz) * 16));
; #pragma unroll
;         for (int j = 0; j < 8; ++j) xf[j] = *(const bf16x8*)(cur + 32768 + (wm * 128 + j * 16 + l15) * 128 + (((ks * 4 + q4) ^ swz) * 16));
; #pragma unroll
;         for (int i = 0; i < 4; ++i)
; #pragma unroll
;           for (int j = 0; j < 8; ++j) acc[i][j] = MFMA16(wf[i], xf[j], acc[i][j]);
;       }
;       vm_wait0();
;       __syncthreads();
;     }
	s_add_u32 s14, s14, 0x80
	s_addc_u32 s15, s15, 0
	s_add_i32 s20, s20, 0x10000
	s_add_i32 s19, s19, 1
	s_cmpk_eq_i32 s14, 0x800
	s_cbranch_scc1 .Lmyg1245_tail
	s_add_i32 s100, s20, 0xffff0000
	s_and_b32 s100, s100, 0x10000
	v_add_u32_e32 v0, s100, v179
	v_add3_u32 v212, v0, v180, v181
	v_add3_u32 v0, v0, v182, v181
	s_cmp_gt_u32 s19, 14
	s_cbranch_scc1 .Lmyg1245_nodma
	s_setprio 3
	s_and_b32 s21, s20, 0x10000
	s_add_i32 s21, s21, 0
	s_add_i32 s22, s21, 0x2000
	s_add_i32 s21, s21, 0xa000
	v_add_u32_e32 v224, s21, v140
	v_lshl_add_u64 v[222:223], v[166:167], 0, s[14:15]
	v_readfirstlane_b32 s23, v224
	v_add_u32_e32 v224, s22, v140
	s_mov_b32 m0, s23
	v_readfirstlane_b32 s23, v224
	v_add_u32_e32 v224, s21, v142
	global_load_lds_dwordx4 v[222:223], off
	v_lshl_add_u64 v[222:223], v[156:157], 0, s[14:15]
	s_mov_b32 m0, s23
	v_readfirstlane_b32 s23, v224
	v_add_u32_e32 v224, s22, v142
	global_load_lds_dwordx4 v[222:223], off
	v_lshl_add_u64 v[222:223], v[164:165], 0, s[14:15]
	s_mov_b32 m0, s23
	v_readfirstlane_b32 s23, v224
	v_add_u32_e32 v224, s21, v144
	global_load_lds_dwordx4 v[222:223], off
	v_lshl_add_u64 v[222:223], v[154:155], 0, s[14:15]
	s_mov_b32 m0, s23
	v_readfirstlane_b32 s23, v224
	v_add_u32_e32 v224, s22, v144
	global_load_lds_dwordx4 v[222:223], off
	v_lshl_add_u64 v[222:223], v[160:161], 0, s[14:15]
	s_mov_b32 m0, s23
	v_readfirstlane_b32 s23, v224
	v_add_u32_e32 v224, s21, v146
	global_load_lds_dwordx4 v[222:223], off
	v_lshl_add_u64 v[222:223], v[152:153], 0, s[14:15]
	s_mov_b32 m0, s23
	v_readfirstlane_b32 s21, v224
	v_add_u32_e32 v224, s22, v146
	global_load_lds_dwordx4 v[222:223], off
	v_lshl_add_u64 v[222:223], v[158:159], 0, s[14:15]
	s_mov_b32 m0, s21
	v_readfirstlane_b32 s21, v224
	global_load_lds_dwordx4 v[222:223], off
	v_lshl_add_u64 v[222:223], v[150:151], 0, s[14:15]
	s_mov_b32 m0, s21
	s_nop 0
	global_load_lds_dwordx4 v[222:223], off
	s_setprio 0
.Lmyg1245_nodma:
	v_mfma_f32_16x16x32_bf16 v[54:57], v[226:229], v[184:187], v[54:57]
	ds_read_b128 v[130:133], v212 offset:8192
	ds_read_b128 v[184:187], v0 offset:43008
	v_mfma_f32_16x16x32_bf16 v[62:65], v[226:229], v[134:137], v[62:65]
	ds_read_b128 v[134:137], v0 offset:40960
	v_mfma_f32_16x16x32_bf16 v[46:49], v[226:229], v[188:191], v[46:49]
	ds_read_b128 v[188:191], v0 offset:45056
	v_mfma_f32_16x16x32_bf16 v[38:41], v[226:229], v[192:195], v[38:41]
	ds_read_b128 v[192:195], v0 offset:47104
	v_mfma_f32_16x16x32_bf16 v[26:29], v[226:229], v[196:199], v[26:29]
	ds_read_b128 v[196:199], v0 offset:49152
	v_mfma_f32_16x16x32_bf16 v[22:25], v[226:229], v[200:203], v[22:25]
	ds_read_b128 v[200:203], v0 offset:51200
	v_mfma_f32_16x16x32_bf16 v[34:37], v[226:229], v[204:207], v[34:37]
	ds_read_b128 v[204:207], v0 offset:53248
	v_mfma_f32_16x16x32_bf16 v[18:21], v[226:229], v[208:211], v[18:21]
	ds_read_b128 v[208:211], v0 offset:55296
	s_branch .Lmyg1245_loop

; #define MFMA16(a, b, c) __builtin_amdgcn_mfma_f32_16x16x32_bf16((a), (b), (c), 0, 0, 0)
; DI void vm_wait0() { asm volatile("s_waitcnt vmcnt(0)" ::: "memory"); }
;   DI unsigned koff(int k) const { return (unsigned)((k >> 6) * EIN + (k & 63)); }
; DI void dma16(const void* g, unsigned char* l) { __builtin_amdgcn_global_load_lds((const unsigned*)g, (lds_u32_t*)(unsigned)(size_t)l, 16, 0, 0); }
; template <class AF, class EF>
; DI void gemm_run(unsigned char* lds, int wv, const AF& af, const bf16_t* __restrict__ Bt, int ldb, int M, int N, int K, const EF& ef, int blk_off) {
;     ...
;     for (int kt = 0; kt < nk; ++kt) {
;       unsigned char* cur = sBase + (kt & 1) * GST;
;       if (kt + 1 < nk) {
;         unsigned char* nxt = sBase + ((kt + 1) & 1) * GST;
;         const int k0 = (kt + 1) << 6;
; #pragma unroll
;         for (int i = 0; i < 4; ++i) {
;           dma16(Ab + aoff[i] + af.koff(k0 + cch), nxt + 32768 + (i * 512 + tid) * 16);
;           dma16(Bt + boff[i] + (unsigned)k0, nxt + (i * 512 + tid) * 16);
;         }
;       }
; #pragma unroll
;       for (int ks = 0; ks < 2; ++ks) {
;         bf16x8 wf[4], xf[8];
; #pragma unroll
;         for (int i = 0; i < 4; ++i) wf[i] = *(const bf16x8*)(cur + (wn * 64 + i * 16 + l15) * 128 + (((ks * 4 + q4) ^ swz) * 16));
; #pragma unroll
;         for (int j = 0; j < 8; ++j) xf[j] = *(const bf16x8*)(cur + 32768 + (wm * 128 + j * 16 + l15) * 128 + (((ks * 4 + q4) ^ swz) * 16));
; #pragma unroll
;         for (int i = 0; i < 4; ++i)
; #pragma unroll
;           for (int j = 0; j < 8; ++j) acc[i][j] = MFMA16(wf[i], xf[j], acc[i][j]);
;       }
;       vm_wait0();
;       __syncthreads();
;     }
.Lmyg1267_loop:
	s_waitcnt lgkmcnt(7)
	v_mfma_f32_16x16x32_bf16 v[126:129], v[130:133], v[180:183], v[126:129]
	ds_read_b128 v[226:229], v179 offset:10240
	s_waitcnt lgkmcnt(7)
	v_mfma_f32_16x16x32_bf16 v[118:121], v[130:133], v[184:187], v[118:121]
	s_waitcnt lgkmcnt(6)
	v_mfma_f32_16x16x32_bf16 v[110:113], v[130:133], v[188:191], v[110:113]
	s_waitcnt lgkmcnt(5)
	v_mfma_f32_16x16x32_bf16 v[102:105], v[130:133], v[192:195], v[102:105]
	s_waitcnt lgkmcnt(4)
	v_mfma_f32_16x16x32_bf16 v[94:97], v[130:133], v[196:199], v[94:97]
	s_waitcnt lgkmcnt(3)
	v_mfma_f32_16x16x32_bf16 v[86:89], v[130:133], v[200:203], v[86:89]
	s_waitcnt lgkmcnt(2)
	v_mfma_f32_16x16x32_bf16 v[78:81], v[130:133], v[204:207], v[78:81]
	s_waitcnt lgkmcnt(1)
	v_mfma_f32_16x16x32_bf16 v[70:73], v[130:133], v[208:211], v[70:73]
	s_waitcnt lgkmcnt(0)
	v_mfma_f32_16x16x32_bf16 v[122:125], v[226:229], v[180:183], v[122:125]
	ds_read_b128 v[130:133], v179 offset:12288
	v_mfma_f32_16x16x32_bf16 v[114:117], v[226:229], v[184:187], v[114:117]
	v_mfma_f32_16x16x32_bf16 v[106:109], v[226:229], v[188:191], v[106:109]
	v_mfma_f32_16x16x32_bf16 v[98:101], v[226:229], v[192:195], v[98:101]
	v_mfma_f32_16x16x32_bf16 v[90:93], v[226:229], v[196:199], v[90:93]
	v_mfma_f32_16x16x32_bf16 v[82:85], v[226:229], v[200:203], v[82:85]
	v_mfma_f32_16x16x32_bf16 v[74:77], v[226:229], v[204:207], v[74:77]
	v_mfma_f32_16x16x32_bf16 v[62:65], v[226:229], v[208:211], v[62:65]
	s_waitcnt lgkmcnt(0)
	v_mfma_f32_16x16x32_bf16 v[54:57], v[130:133], v[180:183], v[54:57]
	ds_read_b128 v[226:229], v179 offset:14336
	v_mfma_f32_16x16x32_bf16 v[46:49], v[130:133], v[184:187], v[46:49]
	v_add_u32_e32 v0, s100, v178
	v_mfma_f32_16x16x32_bf16 v[38:41], v[130:133], v[188:191], v[38:41]
	v_add3_u32 v179, v0, v175, v176
	v_mfma_f32_16x16x32_bf16 v[26:29], v[130:133], v[192:195], v[26:29]
	v_add3_u32 v0, v0, v177, v176
	v_mfma_f32_16x16x32_bf16 v[14:17], v[130:133], v[196:199], v[14:17]
	v_mfma_f32_16x16x32_bf16 v[10:13], v[130:133], v[200:203], v[10:13]
	v_mfma_f32_16x16x32_bf16 v[6:9], v[130:133], v[204:207], v[6:9]
	v_mfma_f32_16x16x32_bf16 v[2:5], v[130:133], v[208:211], v[2:5]
	s_waitcnt lgkmcnt(0)
	v_mfma_f32_16x16x32_bf16 v[66:69], v[226:229], v[180:183], v[66:69]
	ds_read_b128 v[130:133], v179 offset:8192
	ds_read_b128 v[180:183], v0 offset:40960
	v_mfma_f32_16x16x32_bf16 v[58:61], v[226:229], v[184:187], v[58:61]
	ds_read_b128 v[184:187], v0 offset:43008
	v_mfma_f32_16x16x32_bf16 v[50:53], v[226:229], v[188:191], v[50:53]
	ds_read_b128 v[188:191], v0 offset:45056
	v_mfma_f32_16x16x32_bf16 v[42:45], v[226:229], v[192:195], v[42:45]
	ds_read_b128 v[192:195], v0 offset:47104
	v_mfma_f32_16x16x32_bf16 v[30:33], v[226:229], v[196:199], v[30:33]
	ds_read_b128 v[196:199], v0 offset:49152
	v_mfma_f32_16x16x32_bf16 v[22:25], v[226:229], v[200:203], v[22:25]
	ds_read_b128 v[200:203], v0 offset:51200
	v_mfma_f32_16x16x32_bf16 v[18:21], v[226:229], v[204:207], v[18:21]
	ds_read_b128 v[204:207], v0 offset:53248
	v_mfma_f32_16x16x32_bf16 v[34:37], v[226:229], v[208:211], v[34:37]
	ds_read_b128 v[208:211], v0 offset:55296
	s_waitcnt lgkmcnt(7)
	v_mfma_f32_16x16x32_bf16 v[126:129], v[130:133], v[180:183], v[126:129]
	ds_read_b128 v[226:229], v179 offset:10240
	s_waitcnt lgkmcnt(7)
	v_mfma_f32_16x16x32_bf16 v[118:121], v[130:133], v[184:187], v[118:121]
	s_waitcnt lgkmcnt(6)
	v_mfma_f32_16x16x32_bf16 v[110:113], v[130:133], v[188:191], v[110:113]
	s_waitcnt lgkmcnt(5)
	v_mfma_f32_16x16x32_bf16 v[102:105], v[130:133], v[192:195], v[102:105]
	s_waitcnt lgkmcnt(4)
	v_mfma_f32_16x16x32_bf16 v[94:97], v[130:133], v[196:199], v[94:97]
	s_waitcnt lgkmcnt(3)
	v_mfma_f32_16x16x32_bf16 v[86:89], v[130:133], v[200:203], v[86:89]
	s_waitcnt lgkmcnt(2)
	v_mfma_f32_16x16x32_bf16 v[78:81], v[130:133], v[204:207], v[78:81]
	s_waitcnt lgkmcnt(1)
	v_mfma_f32_16x16x32_bf16 v[70:73], v[130:133], v[208:211], v[70:73]
	s_waitcnt lgkmcnt(0)
	v_mfma_f32_16x16x32_bf16 v[122:125], v[226:229], v[180:183], v[122:125]
	ds_read_b128 v[130:133], v179 offset:12288
	v_mfma_f32_16x16x32_bf16 v[114:117], v[226:229], v[184:187], v[114:117]
	v_mfma_f32_16x16x32_bf16 v[106:109], v[226:229], v[188:191], v[106:109]
	v_mfma_f32_16x16x32_bf16 v[98:101], v[226:229], v[192:195], v[98:101]
	v_mfma_f32_16x16x32_bf16 v[90:93], v[226:229], v[196:199], v[90:93]
	v_mfma_f32_16x16x32_bf16 v[82:85], v[226:229], v[200:203], v[82:85]
	v_mfma_f32_16x16x32_bf16 v[74:77], v[226:229], v[204:207], v[74:77]
	v_mfma_f32_16x16x32_bf16 v[62:65], v[226:229], v[208:211], v[62:65]
	s_waitcnt lgkmcnt(0)
	v_mfma_f32_16x16x32_bf16 v[54:57], v[130:133], v[180:183], v[54:57]
	ds_read_b128 v[226:229], v179 offset:14336
	v_mfma_f32_16x16x32_bf16 v[46:49], v[130:133], v[184:187], v[46:49]
	v_mfma_f32_16x16x32_bf16 v[38:41], v[130:133], v[188:191], v[38:41]
	v_mfma_f32_16x16x32_bf16 v[26:29], v[130:133], v[192:195], v[26:29]
	v_mfma_f32_16x16x32_bf16 v[14:17], v[130:133], v[196:199], v[14:17]
	v_mfma_f32_16x16x32_bf16 v[10:13], v[130:133], v[200:203], v[10:13]
	v_mfma_f32_16x16x32_bf16 v[6:9], v[130:133], v[204:207], v[6:9]
	v_mfma_f32_16x16x32_bf16 v[2:5], v[130:133], v[208:211], v[2:5]
	s_waitcnt vmcnt(0) lgkmcnt(0)
	s_barrier
; #define MFMA16(a, b, c) __builtin_amdgcn_mfma_f32_16x16x32_bf16((a), (b), (c), 0, 0, 0)
; DI void vm_wait0() { asm volatile("s_waitcnt vmcnt(0)" ::: "memory"); }
;   DI unsigned koff(int k) const { return (unsigned)((k >> 6) * EIN + (k & 63)); }
; DI void dma16(const void* g, unsigned char* l) { __builtin_amdgcn_global_load_lds((const unsigned*)g, (lds_u32_t*)(unsigned)(size_t)l, 16, 0, 0); }
; template <class AF, class EF>
; DI void gemm_run(unsigned char* lds, int wv, const AF& af, const bf16_t* __restrict__ Bt, int ldb, int M, int N, int K, const EF& ef, int blk_off) {
;     ...
;     for (int kt = 0; kt < nk; ++kt) {
;       unsigned char* cur = sBase + (kt & 1) * GST;
;       if (kt + 1 < nk) {
;         unsigned char* nxt = sBase + ((kt + 1) & 1) * GST;
;         const int k0 = (kt + 1) << 6;
; #pragma unroll
;         for (int i = 0; i < 4; ++i) {
;           dma16(Ab + aoff[i] + af.koff(k0 + cch), nxt + 32768 + (i * 512 + tid) * 16);
;           dma16(Bt + boff[i] + (unsigned)k0, nxt + (i * 512 + tid) * 16);
;         }
;       }
; #pragma unroll
;       for (int ks = 0; ks < 2; ++ks) {
;         bf16x8 wf[4], xf[8];
; #pragma unroll
;         for (int i = 0; i < 4; ++i) wf[i] = *(const bf16x8*)(cur + (wn * 64 + i * 16 + l15) * 128 + (((ks * 4 + q4) ^ swz) * 16));
; #pragma unroll
;         for (int j = 0; j < 8; ++j) xf[j] = *(const bf16x8*)(cur + 32768 + (wm * 128 + j * 16 + l15) * 128 + (((ks * 4 + q4) ^ swz) * 16));
; #pragma unroll
;         for (int i = 0; i < 4; ++i)
; #pragma unroll
;           for (int j = 0; j < 8; ++j) acc[i][j] = MFMA16(wf[i], xf[j], acc[i][j]);
;       }
;       vm_wait0();
;       __syncthreads();
;     }
	s_add_u32 s10, s10, 0x80
	s_addc_u32 s11, s11, 0
	s_add_i32 s15, s15, 0x10000
	s_cmpk_eq_i32 s10, 0x800
	s_cbranch_scc1 .Lmyg1267_tail
	s_add_i32 s100, s15, 0xffff0000
	s_and_b32 s100, s100, 0x10000
	v_add_u32_e32 v0, s100, v174
	v_add3_u32 v179, v0, v175, v176
	v_add3_u32 v0, v0, v177, v176
	s_cmpk_eq_i32 s10, 0x780
	s_cbranch_scc1 .Lmyg1267_nodma
	s_setprio 3
	s_and_b32 s16, s15, 0x10000
	s_add_i32 s16, s16, 0
	s_add_i32 s17, s16, 0x2000
	s_add_i32 s16, s16, 0xa000
	v_add_u32_e32 v224, s16, v136
	v_lshl_add_u64 v[222:223], v[160:161], 0, s[10:11]
	v_readfirstlane_b32 s18, v224
	v_add_u32_e32 v224, s17, v136
	s_mov_b32 m0, s18
	v_readfirstlane_b32 s18, v224
	v_add_u32_e32 v224, s16, v138
	global_load_lds_dwordx4 v[222:223], off
	v_lshl_add_u64 v[222:223], v[152:153], 0, s[10:11]
	s_mov_b32 m0, s18
	v_readfirstlane_b32 s18, v224
	v_add_u32_e32 v224, s17, v138
	global_load_lds_dwordx4 v[222:223], off
	v_lshl_add_u64 v[222:223], v[158:159], 0, s[10:11]
	s_mov_b32 m0, s18
	v_readfirstlane_b32 s18, v224
	v_add_u32_e32 v224, s16, v140
	global_load_lds_dwordx4 v[222:223], off
	v_lshl_add_u64 v[222:223], v[150:151], 0, s[10:11]
	s_mov_b32 m0, s18
	v_readfirstlane_b32 s18, v224
	v_add_u32_e32 v224, s17, v140
	global_load_lds_dwordx4 v[222:223], off
	v_lshl_add_u64 v[222:223], v[156:157], 0, s[10:11]
	s_mov_b32 m0, s18
	v_readfirstlane_b32 s18, v224
	v_add_u32_e32 v224, s16, v142
	global_load_lds_dwordx4 v[222:223], off
	v_lshl_add_u64 v[222:223], v[148:149], 0, s[10:11]
	s_mov_b32 m0, s18
	v_readfirstlane_b32 s16, v224
	v_add_u32_e32 v224, s17, v142
	global_load_lds_dwordx4 v[222:223], off
	v_lshl_add_u64 v[222:223], v[154:155], 0, s[10:11]
	s_mov_b32 m0, s16
	v_readfirstlane_b32 s16, v224
	global_load_lds_dwordx4 v[222:223], off
	v_lshl_add_u64 v[222:223], v[146:147], 0, s[10:11]
	s_mov_b32 m0, s16
	s_nop 0
	global_load_lds_dwordx4 v[222:223], off
	s_setprio 0
.Lmyg1267_nodma:
	v_mfma_f32_16x16x32_bf16 v[66:69], v[226:229], v[180:183], v[66:69]
	ds_read_b128 v[130:133], v179 offset:8192
	ds_read_b128 v[180:183], v0 offset:40960
	v_mfma_f32_16x16x32_bf16 v[58:61], v[226:229], v[184:187], v[58:61]
	ds_read_b128 v[184:187], v0 offset:43008
	v_mfma_f32_16x16x32_bf16 v[50:53], v[226:229], v[188:191], v[50:53]
	ds_read_b128 v[188:191], v0 offset:45056
	v_mfma_f32_16x16x32_bf16 v[42:45], v[226:229], v[192:195], v[42:45]
	ds_read_b128 v[192:195], v0 offset:47104
	v_mfma_f32_16x16x32_bf16 v[30:33], v[226:229], v[196:199], v[30:33]
	ds_read_b128 v[196:199], v0 offset:49152
	v_mfma_f32_16x16x32_bf16 v[22:25], v[226:229], v[200:203], v[22:25]
	ds_read_b128 v[200:203], v0 offset:51200
	v_mfma_f32_16x16x32_bf16 v[18:21], v[226:229], v[204:207], v[18:21]
	ds_read_b128 v[204:207], v0 offset:53248
	v_mfma_f32_16x16x32_bf16 v[34:37], v[226:229], v[208:211], v[34:37]
	ds_read_b128 v[208:211], v0 offset:55296
	s_branch .Lmyg1267_loop

; #define MFMA16(a, b, c) __builtin_amdgcn_mfma_f32_16x16x32_bf16((a), (b), (c), 0, 0, 0)
; DI void vm_wait0() { asm volatile("s_waitcnt vmcnt(0)" ::: "memory"); }
;   DI unsigned koff(int k) const { return (unsigned)((k >> 6) * EIN + (k & 63)); }
; DI void dma16(const void* g, unsigned char* l) { __builtin_amdgcn_global_load_lds((const unsigned*)g, (lds_u32_t*)(unsigned)(size_t)l, 16, 0, 0); }
; template <class AF, class EF>
; DI void gemm_run(unsigned char* lds, int wv, const AF& af, const bf16_t* __restrict__ Bt, int ldb, int M, int N, int K, const EF& ef, int blk_off) {
;     ...
;     for (int kt = 0; kt < nk; ++kt) {
;       unsigned char* cur = sBase + (kt & 1) * GST;
;       if (kt + 1 < nk) {
;         unsigned char* nxt = sBase + ((kt + 1) & 1) * GST;
;         const int k0 = (kt + 1) << 6;
; #pragma unroll
;         for (int i = 0; i < 4; ++i) {
;           dma16(Ab + aoff[i] + af.koff(k0 + cch), nxt + 32768 + (i * 512 + tid) * 16);
;           dma16(Bt + boff[i] + (unsigned)k0, nxt + (i * 512 + tid) * 16);
;         }
;       }
; #pragma unroll
;       for (int ks = 0; ks < 2; ++ks) {
;         bf16x8 wf[4], xf[8];
; #pragma unroll
;         for (int i = 0; i < 4; ++i) wf[i] = *(const bf16x8*)(cur + (wn * 64 + i * 16 + l15) * 128 + (((ks * 4 + q4) ^ swz) * 16));
; #pragma unroll
;         for (int j = 0; j < 8; ++j) xf[j] = *(const bf16x8*)(cur + 32768 + (wm * 128 + j * 16 + l15) * 128 + (((ks * 4 + q4) ^ swz) * 16));
; #pragma unroll
;         for (int i = 0; i < 4; ++i)
; #pragma unroll
;           for (int j = 0; j < 8; ++j) acc[i][j] = MFMA16(wf[i], xf[j], acc[i][j]);
;       }
;       vm_wait0();
;       __syncthreads();
;     }
.Lmyg1279_loop:
	s_waitcnt lgkmcnt(7)
	v_mfma_f32_16x16x32_bf16 v[118:121], v[130:133], v[184:187], v[118:121]
	ds_read_b128 v[226:229], v212 offset:10240
	s_waitcnt lgkmcnt(7)
	v_mfma_f32_16x16x32_bf16 v[126:129], v[130:133], v[134:137], v[126:129]
	s_waitcnt lgkmcnt(6)
	v_mfma_f32_16x16x32_bf16 v[110:113], v[130:133], v[188:191], v[110:113]
	s_waitcnt lgkmcnt(5)
	v_mfma_f32_16x16x32_bf16 v[102:105], v[130:133], v[192:195], v[102:105]
	s_waitcnt lgkmcnt(4)
	v_mfma_f32_16x16x32_bf16 v[94:97], v[130:133], v[196:199], v[94:97]
	s_waitcnt lgkmcnt(3)
	v_mfma_f32_16x16x32_bf16 v[86:89], v[130:133], v[200:203], v[86:89]
	s_waitcnt lgkmcnt(2)
	v_mfma_f32_16x16x32_bf16 v[78:81], v[130:133], v[204:207], v[78:81]
	s_waitcnt lgkmcnt(1)
	v_mfma_f32_16x16x32_bf16 v[70:73], v[130:133], v[208:211], v[70:73]
	s_waitcnt lgkmcnt(0)
	v_mfma_f32_16x16x32_bf16 v[122:125], v[226:229], v[134:137], v[122:125]
	ds_read_b128 v[130:133], v212 offset:12288
	v_mfma_f32_16x16x32_bf16 v[114:117], v[226:229], v[184:187], v[114:117]
	v_mfma_f32_16x16x32_bf16 v[106:109], v[226:229], v[188:191], v[106:109]
	v_mfma_f32_16x16x32_bf16 v[98:101], v[226:229], v[192:195], v[98:101]
	v_mfma_f32_16x16x32_bf16 v[90:93], v[226:229], v[196:199], v[90:93]
	v_mfma_f32_16x16x32_bf16 v[82:85], v[226:229], v[200:203], v[82:85]
	v_mfma_f32_16x16x32_bf16 v[74:77], v[226:229], v[204:207], v[74:77]
	v_mfma_f32_16x16x32_bf16 v[66:69], v[226:229], v[208:211], v[66:69]
	s_waitcnt lgkmcnt(0)
	v_mfma_f32_16x16x32_bf16 v[58:61], v[130:133], v[134:137], v[58:61]
	ds_read_b128 v[226:229], v212 offset:14336
	v_mfma_f32_16x16x32_bf16 v[50:53], v[130:133], v[184:187], v[50:53]
	v_add_u32_e32 v0, s100, v183
	v_mfma_f32_16x16x32_bf16 v[42:45], v[130:133], v[188:191], v[42:45]
	v_add3_u32 v212, v0, v180, v181
	v_mfma_f32_16x16x32_bf16 v[30:33], v[130:133], v[192:195], v[30:33]
	v_add3_u32 v0, v0, v182, v181
	v_mfma_f32_16x16x32_bf16 v[14:17], v[130:133], v[196:199], v[14:17]
	v_mfma_f32_16x16x32_bf16 v[10:13], v[130:133], v[200:203], v[10:13]
	v_mfma_f32_16x16x32_bf16 v[6:9], v[130:133], v[204:207], v[6:9]
	v_mfma_f32_16x16x32_bf16 v[2:5], v[130:133], v[208:211], v[2:5]
	s_waitcnt lgkmcnt(0)
	v_mfma_f32_16x16x32_bf16 v[54:57], v[226:229], v[184:187], v[54:57]
	ds_read_b128 v[130:133], v212 offset:8192
	ds_read_b128 v[184:187], v0 offset:43008
	v_mfma_f32_16x16x32_bf16 v[62:65], v[226:229], v[134:137], v[62:65]
	ds_read_b128 v[134:137], v0 offset:40960
	v_mfma_f32_16x16x32_bf16 v[46:49], v[226:229], v[188:191], v[46:49]
	ds_read_b128 v[188:191], v0 offset:45056
	v_mfma_f32_16x16x32_bf16 v[38:41], v[226:229], v[192:195], v[38:41]
	ds_read_b128 v[192:195], v0 offset:47104
	v_mfma_f32_16x16x32_bf16 v[26:29], v[226:229], v[196:199], v[26:29]
	ds_read_b128 v[196:199], v0 offset:49152
	v_mfma_f32_16x16x32_bf16 v[22:25], v[226:229], v[200:203], v[22:25]
	ds_read_b128 v[200:203], v0 offset:51200
	v_mfma_f32_16x16x32_bf16 v[34:37], v[226:229], v[204:207], v[34:37]
	ds_read_b128 v[204:207], v0 offset:53248
	v_mfma_f32_16x16x32_bf16 v[18:21], v[226:229], v[208:211], v[18:21]
	ds_read_b128 v[208:211], v0 offset:55296
	s_waitcnt lgkmcnt(7)
	v_mfma_f32_16x16x32_bf16 v[118:121], v[130:133], v[184:187], v[118:121]
	ds_read_b128 v[226:229], v212 offset:10240
	s_waitcnt lgkmcnt(7)
	v_mfma_f32_16x16x32_bf16 v[126:129], v[130:133], v[134:137], v[126:129]
	s_waitcnt lgkmcnt(6)
	v_mfma_f32_16x16x32_bf16 v[110:113], v[130:133], v[188:191], v[110:113]
	s_waitcnt lgkmcnt(5)
	v_mfma_f32_16x16x32_bf16 v[102:105], v[130:133], v[192:195], v[102:105]
	s_waitcnt lgkmcnt(4)
	v_mfma_f32_16x16x32_bf16 v[94:97], v[130:133], v[196:199], v[94:97]
	s_waitcnt lgkmcnt(3)
	v_mfma_f32_16x16x32_bf16 v[86:89], v[130:133], v[200:203], v[86:89]
	s_waitcnt lgkmcnt(2)
	v_mfma_f32_16x16x32_bf16 v[78:81], v[130:133], v[204:207], v[78:81]
	s_waitcnt lgkmcnt(1)
	v_mfma_f32_16x16x32_bf16 v[70:73], v[130:133], v[208:211], v[70:73]
	s_waitcnt lgkmcnt(0)
	v_mfma_f32_16x16x32_bf16 v[122:125], v[226:229], v[134:137], v[122:125]
	ds_read_b128 v[130:133], v212 offset:12288
	v_mfma_f32_16x16x32_bf16 v[114:117], v[226:229], v[184:187], v[114:117]
	v_mfma_f32_16x16x32_bf16 v[106:109], v[226:229], v[188:191], v[106:109]
	v_mfma_f32_16x16x32_bf16 v[98:101], v[226:229], v[192:195], v[98:101]
	v_mfma_f32_16x16x32_bf16 v[90:93], v[226:229], v[196:199], v[90:93]
	v_mfma_f32_16x16x32_bf16 v[82:85], v[226:229], v[200:203], v[82:85]
	v_mfma_f32_16x16x32_bf16 v[74:77], v[226:229], v[204:207], v[74:77]
	v_mfma_f32_16x16x32_bf16 v[66:69], v[226:229], v[208:211], v[66:69]
	s_waitcnt lgkmcnt(0)
	v_mfma_f32_16x16x32_bf16 v[58:61], v[130:133], v[134:137], v[58:61]
	ds_read_b128 v[226:229], v212 offset:14336
	v_mfma_f32_16x16x32_bf16 v[50:53], v[130:133], v[184:187], v[50:53]
	v_mfma_f32_16x16x32_bf16 v[42:45], v[130:133], v[188:191], v[42:45]
	v_mfma_f32_16x16x32_bf16 v[30:33], v[130:133], v[192:195], v[30:33]
	v_mfma_f32_16x16x32_bf16 v[14:17], v[130:133], v[196:199], v[14:17]
	v_mfma_f32_16x16x32_bf16 v[10:13], v[130:133], v[200:203], v[10:13]
	v_mfma_f32_16x16x32_bf16 v[6:9], v[130:133], v[204:207], v[6:9]
	v_mfma_f32_16x16x32_bf16 v[2:5], v[130:133], v[208:211], v[2:5]
	s_waitcnt vmcnt(0) lgkmcnt(0)
	s_barrier
; #define MFMA16(a, b, c) __builtin_amdgcn_mfma_f32_16x16x32_bf16((a), (b), (c), 0, 0, 0)
; DI void vm_wait0() { asm volatile("s_waitcnt vmcnt(0)" ::: "memory"); }
;   DI unsigned koff(int k) const { return (unsigned)((k >> 6) * EIN + (k & 63)); }
; DI void dma16(const void* g, unsigned char* l) { __builtin_amdgcn_global_load_lds((const unsigned*)g, (lds_u32_t*)(unsigned)(size_t)l, 16, 0, 0); }
; template <class AF, class EF>
; DI void gemm_run(unsigned char* lds, int wv, const AF& af, const bf16_t* __restrict__ Bt, int ldb, int M, int N, int K, const EF& ef, int blk_off) {
;     ...
;     for (int kt = 0; kt < nk; ++kt) {
;       unsigned char* cur = sBase + (kt & 1) * GST;
;       if (kt + 1 < nk) {
;         unsigned char* nxt = sBase + ((kt + 1) & 1) * GST;
;         const int k0 = (kt + 1) << 6;
; #pragma unroll
;         for (int i = 0; i < 4; ++i) {
;           dma16(Ab + aoff[i] + af.koff(k0 + cch), nxt + 32768 + (i * 512 + tid) * 16);
;           dma16(Bt + boff[i] + (unsigned)k0, nxt + (i * 512 + tid) * 16);
;         }
;       }
; #pragma unroll
;       for (int ks = 0; ks < 2; ++ks) {
;         bf16x8 wf[4], xf[8];
; #pragma unroll
;         for (int i = 0; i < 4; ++i) wf[i] = *(const bf16x8*)(cur + (wn * 64 + i * 16 + l15) * 128 + (((ks * 4 + q4) ^ swz) * 16));
; #pragma unroll
;         for (int j = 0; j < 8; ++j) xf[j] = *(const bf16x8*)(cur + 32768 + (wm * 128 + j * 16 + l15) * 128 + (((ks * 4 + q4) ^ swz) * 16));
; #pragma unroll
;         for (int i = 0; i < 4; ++i)
; #pragma unroll
;           for (int j = 0; j < 8; ++j) acc[i][j] = MFMA16(wf[i], xf[j], acc[i][j]);
;       }
;       vm_wait0();
;       __syncthreads();
;     }
	s_add_u32 s16, s16, 0x80
	s_addc_u32 s17, s17, 0
	s_add_i32 s22, s22, 0x10000
	s_add_i32 s21, s21, 1
	s_cmpk_eq_i32 s16, 0x2000
	s_cbranch_scc1 .Lmyg1279_tail
	s_add_i32 s100, s22, 0xffff0000
	s_and_b32 s100, s100, 0x10000
	v_add_u32_e32 v0, s100, v179
	v_add3_u32 v212, v0, v180, v181
	v_add3_u32 v0, v0, v182, v181
	s_cmp_gt_u32 s21, 62
	s_cbranch_scc1 .Lmyg1279_nodma
	s_setprio 3
	s_and_b32 s23, s22, 0x10000
	s_add_i32 s23, s23, 0
	s_add_i32 s24, s23, 0x2000
	s_add_i32 s23, s23, 0xa000
	v_add_u32_e32 v224, s23, v140
	v_lshl_add_u64 v[222:223], v[166:167], 0, s[16:17]
	v_readfirstlane_b32 s25, v224
	v_add_u32_e32 v224, s24, v140
	s_mov_b32 m0, s25
	v_readfirstlane_b32 s25, v224
	v_add_u32_e32 v224, s23, v142
	global_load_lds_dwordx4 v[222:223], off
	v_lshl_add_u64 v[222:223], v[156:157], 0, s[16:17]
	s_mov_b32 m0, s25
	v_readfirstlane_b32 s25, v224
	v_add_u32_e32 v224, s24, v142
	global_load_lds_dwordx4 v[222:223], off
	v_lshl_add_u64 v[222:223], v[164:165], 0, s[16:17]
	s_mov_b32 m0, s25
	v_readfirstlane_b32 s25, v224
	v_add_u32_e32 v224, s23, v144
	global_load_lds_dwordx4 v[222:223], off
	v_lshl_add_u64 v[222:223], v[154:155], 0, s[16:17]
	s_mov_b32 m0, s25
	v_readfirstlane_b32 s25, v224
	v_add_u32_e32 v224, s24, v144
	global_load_lds_dwordx4 v[222:223], off
	v_lshl_add_u64 v[222:223], v[160:161], 0, s[16:17]
	s_mov_b32 m0, s25
	v_readfirstlane_b32 s25, v224
	v_add_u32_e32 v224, s23, v146
	global_load_lds_dwordx4 v[222:223], off
	v_lshl_add_u64 v[222:223], v[152:153], 0, s[16:17]
	s_mov_b32 m0, s25
	v_readfirstlane_b32 s23, v224
	v_add_u32_e32 v224, s24, v146
	global_load_lds_dwordx4 v[222:223], off
	v_lshl_add_u64 v[222:223], v[158:159], 0, s[16:17]
	s_mov_b32 m0, s23
	v_readfirstlane_b32 s23, v224
	global_load_lds_dwordx4 v[222:223], off
	v_lshl_add_u64 v[222:223], v[150:151], 0, s[16:17]
	s_mov_b32 m0, s23
	s_nop 0
	global_load_lds_dwordx4 v[222:223], off
	s_setprio 0
